# nt on the converted p (bf16) stores inside the scan loop
# speedup vs baseline: 1.0087x; 1.0087x over previous
; #define LAS __attribute__((address_space(3)))
; __device__ __forceinline__ unsigned cvt_pk_bf16(float lo, float hi) { const f32x2 v = {lo, hi}; return __builtin_bit_cast(unsigned, __builtin_convertvector(v, bfx2_t)); }
; __device__ __forceinline__ void conv_p(const Params& P, int l) {
;     ...
;     for (; i + 3 * stride < n8; i += 4 * stride) {
;         f32x4 a[4], b[4];
; #pragma unroll
;         for (int q = 0; q < 4; ++q) { a[q] = *(const f32x4*)(src + (i + q * stride) * 8); b[q] = *(const f32x4*)(src + (i + q * stride) * 8 + 4); }
; #pragma unroll
;         for (int q = 0; q < 4; ++q) { u32x4 w; w.x = cvt_pk_bf16(a[q][0], a[q][1]); w.y = cvt_pk_bf16(a[q][2], a[q][3]); w.z = cvt_pk_bf16(b[q][0], b[q][1]); w.w = cvt_pk_bf16(b[q][2], b[q][3]);
;             *(u32x4*)(dst + (i + q * stride) * 8) = w; }
; template <int PASS> __device__ void ssm_pass(const Params& P, int l, LAS unsigned char* lds) {
;     ...
;         for (int mt = 0; mt < 64; ++mt) {
;             u32x2 unext = ucur; if (mt < 63) unext = *(const u32x2*)(zrow + (size_t)(mt + 1) * 16 * DM);
;             const bf16x4 af = __builtin_bit_cast(bf16x4, ucur);
;             f32x4 d[8];
; #pragma unroll
;             for (int t = 0; t < 8; ++t) d[t] = __builtin_amdgcn_mfma_f32_16x16x16bf16_1k(af, bf[t], (f32x4){0.f, 0.f, 0.f, 0.f}, 0, 0, 0);
; #pragma unroll
;             for (int tq = 0; tq < 4; ++tq)
; #pragma unroll
;                 for (int j = 0; j < 4; ++j) *(LAS f32x2*)(BU + (4 * fq + j) * 528 + (16 * tq + fr) * 8) = (f32x2){d[tq][j], d[tq + 4][j]};
;             asm volatile("s_waitcnt lgkmcnt(0)" ::: "memory");
; #pragma unroll
;             for (int j = 0; j < 16; ++j) {
;                 const f32x2 bu = *(const LAS f32x2*)(BU + j * 528 + lane * 8);
;                 sv = __builtin_elementwise_fma(ayn, __builtin_shufflevector(sv, sv, 1, 0), __builtin_elementwise_fma(axx, sv, bu));
;                 if (PASS == 2) *(LAS unsigned*)(SI + j * 272 + lane * 4) = cvt_pk_bf16(sv.x, sv.y);
;             }
.Lp1_loop:
	s_waitcnt vmcnt(9)
	ds_write_b64 v146, v[40:41]
	ds_read_b128 v[156:159], v196
	ds_read_b128 v[200:203], v197
	global_load_dwordx2 v[50:51], v[54:55], off
	v_lshl_add_u64 v[54:55], v[54:55], 0, s[20:21]
	global_load_dwordx4 v[60:63], v[56:57], off nt
	v_fma_f32 v70, v30, v34, v88
	v_fma_f32 v71, v30, v35, v104
	v_fma_f32 v72, v10, v35, v70
	v_fma_f32 v73, v11, v34, v71
	v_fma_f32 v70, v30, v72, v89
	v_fma_f32 v71, v30, v73, v105
	v_fma_f32 v34, v10, v73, v70
	v_fma_f32 v35, v11, v72, v71
	v_fma_f32 v70, v30, v34, v90
	v_fma_f32 v71, v30, v35, v106
	v_fma_f32 v72, v10, v35, v70
	v_fma_f32 v73, v11, v34, v71
	v_fma_f32 v70, v30, v72, v91
	v_fma_f32 v71, v30, v73, v107
	v_fma_f32 v34, v10, v73, v70
	v_fma_f32 v35, v11, v72, v71
	s_waitcnt lgkmcnt(0)
	v_mfma_f32_32x32x16_bf16 v[120:135], v[156:159], v[12:15], 0
	v_mfma_f32_32x32x16_bf16 v[226:241], v[156:159], v[20:23], 0
	v_fma_f32 v70, v30, v34, v92
	v_fma_f32 v71, v30, v35, v108
	v_fma_f32 v72, v10, v35, v70
	v_fma_f32 v73, v11, v34, v71
	v_fma_f32 v70, v30, v72, v93
	v_fma_f32 v71, v30, v73, v109
	v_fma_f32 v34, v10, v73, v70
	v_fma_f32 v35, v11, v72, v71
	v_fma_f32 v70, v30, v34, v94
	v_fma_f32 v71, v30, v35, v110
	v_fma_f32 v72, v10, v35, v70
	v_fma_f32 v73, v11, v34, v71
	v_fma_f32 v70, v30, v72, v95
	v_fma_f32 v71, v30, v73, v111
	v_fma_f32 v34, v10, v73, v70
	v_fma_f32 v35, v11, v72, v71
	v_mfma_f32_32x32x16_bf16 v[120:135], v[200:203], v[16:19], v[120:135]
	v_mfma_f32_32x32x16_bf16 v[226:241], v[200:203], v[24:27], v[226:241]
	v_fma_f32 v70, v30, v34, v96
	v_fma_f32 v71, v30, v35, v112
	v_fma_f32 v72, v10, v35, v70
	v_fma_f32 v73, v11, v34, v71
	v_fma_f32 v70, v30, v72, v97
	v_fma_f32 v71, v30, v73, v113
	v_fma_f32 v34, v10, v73, v70
	v_fma_f32 v35, v11, v72, v71
	v_fma_f32 v70, v30, v34, v98
	v_fma_f32 v71, v30, v35, v114
	v_fma_f32 v72, v10, v35, v70
	v_fma_f32 v73, v11, v34, v71
	v_fma_f32 v70, v30, v72, v99
	v_fma_f32 v71, v30, v73, v115
	v_fma_f32 v34, v10, v73, v70
	v_fma_f32 v35, v11, v72, v71
	v_fma_f32 v70, v30, v34, v100
	v_fma_f32 v71, v30, v35, v116
	v_fma_f32 v72, v10, v35, v70
	v_fma_f32 v73, v11, v34, v71
	v_fma_f32 v70, v30, v72, v101
	v_fma_f32 v71, v30, v73, v117
	v_fma_f32 v34, v10, v73, v70
	v_fma_f32 v35, v11, v72, v71
	v_fma_f32 v70, v30, v34, v102
	v_fma_f32 v71, v30, v35, v118
	v_fma_f32 v72, v10, v35, v70
	v_fma_f32 v73, v11, v34, v71
	v_fma_f32 v70, v30, v72, v103
	v_fma_f32 v71, v30, v73, v119
	v_fma_f32 v34, v10, v73, v70
	v_fma_f32 v35, v11, v72, v71
	s_waitcnt vmcnt(9)
	ds_write_b64 v146, v[42:43]
	ds_read_b128 v[156:159], v196
	ds_read_b128 v[200:203], v197
	global_load_dwordx2 v[52:53], v[54:55], off
	v_lshl_add_u64 v[54:55], v[54:55], 0, s[20:21]
	global_load_dwordx4 v[64:67], v[56:57], off offset:16 nt
	s_mov_b64 s[22:23], 0x400000
	v_lshl_add_u64 v[56:57], v[56:57], 0, s[22:23]
	v_fma_f32 v70, v30, v34, v120
	v_fma_f32 v71, v30, v35, v226
	v_fma_f32 v72, v10, v35, v70
	v_fma_f32 v73, v11, v34, v71
	v_fma_f32 v70, v30, v72, v121
	v_fma_f32 v71, v30, v73, v227
	v_fma_f32 v34, v10, v73, v70
	v_fma_f32 v35, v11, v72, v71
	v_fma_f32 v70, v30, v34, v122
	v_fma_f32 v71, v30, v35, v228
	v_fma_f32 v72, v10, v35, v70
	v_fma_f32 v73, v11, v34, v71
	v_fma_f32 v70, v30, v72, v123
	v_fma_f32 v71, v30, v73, v229
	v_fma_f32 v34, v10, v73, v70
	v_fma_f32 v35, v11, v72, v71
	s_waitcnt lgkmcnt(0)
; #define LAS __attribute__((address_space(3)))
; __device__ __forceinline__ unsigned cvt_pk_bf16(float lo, float hi) { const f32x2 v = {lo, hi}; return __builtin_bit_cast(unsigned, __builtin_convertvector(v, bfx2_t)); }
; __device__ __forceinline__ void conv_p(const Params& P, int l) {
;     ...
;         for (int q = 0; q < 4; ++q) { a[q] = *(const f32x4*)(src + (i + q * stride) * 8); b[q] = *(const f32x4*)(src + (i + q * stride) * 8 + 4); }
; #pragma unroll
;         for (int q = 0; q < 4; ++q) { u32x4 w; w.x = cvt_pk_bf16(a[q][0], a[q][1]); w.y = cvt_pk_bf16(a[q][2], a[q][3]); w.z = cvt_pk_bf16(b[q][0], b[q][1]); w.w = cvt_pk_bf16(b[q][2], b[q][3]);
;             *(u32x4*)(dst + (i + q * stride) * 8) = w; }
; template <int PASS> __device__ void ssm_pass(const Params& P, int l, LAS unsigned char* lds) {
;     ...
;         for (int mt = 0; mt < 64; ++mt) {
;             u32x2 unext = ucur; if (mt < 63) unext = *(const u32x2*)(zrow + (size_t)(mt + 1) * 16 * DM);
;             const bf16x4 af = __builtin_bit_cast(bf16x4, ucur);
;             f32x4 d[8];
; #pragma unroll
;             for (int t = 0; t < 8; ++t) d[t] = __builtin_amdgcn_mfma_f32_16x16x16bf16_1k(af, bf[t], (f32x4){0.f, 0.f, 0.f, 0.f}, 0, 0, 0);
; #pragma unroll
;             for (int tq = 0; tq < 4; ++tq)
; #pragma unroll
;                 for (int j = 0; j < 4; ++j) *(LAS f32x2*)(BU + (4 * fq + j) * 528 + (16 * tq + fr) * 8) = (f32x2){d[tq][j], d[tq + 4][j]};
;             asm volatile("s_waitcnt lgkmcnt(0)" ::: "memory");
; #pragma unroll
;             for (int j = 0; j < 16; ++j) {
;                 const f32x2 bu = *(const LAS f32x2*)(BU + j * 528 + lane * 8);
;                 sv = __builtin_elementwise_fma(ayn, __builtin_shufflevector(sv, sv, 1, 0), __builtin_elementwise_fma(axx, sv, bu));
;                 if (PASS == 2) *(LAS unsigned*)(SI + j * 272 + lane * 4) = cvt_pk_bf16(sv.x, sv.y);
;             }
	v_mfma_f32_32x32x16_bf16 v[88:103], v[156:159], v[12:15], 0
	v_mfma_f32_32x32x16_bf16 v[104:119], v[156:159], v[20:23], 0
	v_fma_f32 v70, v30, v34, v124
	v_fma_f32 v71, v30, v35, v230
	v_fma_f32 v72, v10, v35, v70
	v_fma_f32 v73, v11, v34, v71
	v_fma_f32 v70, v30, v72, v125
	v_fma_f32 v71, v30, v73, v231
	v_fma_f32 v34, v10, v73, v70
	v_fma_f32 v35, v11, v72, v71
	v_fma_f32 v70, v30, v34, v126
	v_fma_f32 v71, v30, v35, v232
	v_fma_f32 v72, v10, v35, v70
	v_fma_f32 v73, v11, v34, v71
	v_fma_f32 v70, v30, v72, v127
	v_fma_f32 v71, v30, v73, v233
	v_fma_f32 v34, v10, v73, v70
	v_fma_f32 v35, v11, v72, v71
	v_mfma_f32_32x32x16_bf16 v[88:103], v[200:203], v[16:19], v[88:103]
	v_mfma_f32_32x32x16_bf16 v[104:119], v[200:203], v[24:27], v[104:119]
	v_fma_f32 v70, v30, v34, v128
	v_fma_f32 v71, v30, v35, v234
	v_fma_f32 v72, v10, v35, v70
	v_fma_f32 v73, v11, v34, v71
	v_fma_f32 v70, v30, v72, v129
	v_fma_f32 v71, v30, v73, v235
	v_fma_f32 v34, v10, v73, v70
	v_fma_f32 v35, v11, v72, v71
	v_fma_f32 v70, v30, v34, v130
	v_fma_f32 v71, v30, v35, v236
	v_fma_f32 v72, v10, v35, v70
	v_fma_f32 v73, v11, v34, v71
	v_fma_f32 v70, v30, v72, v131
	v_fma_f32 v71, v30, v73, v237
	v_fma_f32 v34, v10, v73, v70
	v_fma_f32 v35, v11, v72, v71
	v_fma_f32 v70, v30, v34, v132
	v_fma_f32 v71, v30, v35, v238
	v_fma_f32 v72, v10, v35, v70
	v_fma_f32 v73, v11, v34, v71
	v_fma_f32 v70, v30, v72, v133
	v_fma_f32 v71, v30, v73, v239
	v_fma_f32 v34, v10, v73, v70
	v_fma_f32 v35, v11, v72, v71
	v_fma_f32 v70, v30, v34, v134
	v_fma_f32 v71, v30, v35, v240
	v_fma_f32 v72, v10, v35, v70
	v_fma_f32 v73, v11, v34, v71
	v_fma_f32 v70, v30, v72, v135
	v_fma_f32 v71, v30, v73, v241
	v_fma_f32 v34, v10, v73, v70
	v_fma_f32 v35, v11, v72, v71
	s_waitcnt vmcnt(9)
	ds_write_b64 v146, v[44:45]
	ds_read_b128 v[156:159], v196
	ds_read_b128 v[200:203], v197
	global_load_dwordx2 v[36:37], v[54:55], off
	v_lshl_add_u64 v[54:55], v[54:55], 0, s[20:21]
	global_load_dwordx2 v[144:145], v[54:55], off
	v_fma_f32 v70, v30, v34, v88
	v_fma_f32 v71, v30, v35, v104
	v_fma_f32 v72, v10, v35, v70
	v_fma_f32 v73, v11, v34, v71
	v_fma_f32 v70, v30, v72, v89
	v_fma_f32 v71, v30, v73, v105
	v_fma_f32 v34, v10, v73, v70
	v_fma_f32 v35, v11, v72, v71
	v_fma_f32 v70, v30, v34, v90
	v_fma_f32 v71, v30, v35, v106
	v_fma_f32 v72, v10, v35, v70
	v_fma_f32 v73, v11, v34, v71
	v_fma_f32 v70, v30, v72, v91
	v_fma_f32 v71, v30, v73, v107
	v_fma_f32 v34, v10, v73, v70
	v_fma_f32 v35, v11, v72, v71
	s_waitcnt lgkmcnt(0)
	v_mfma_f32_32x32x16_bf16 v[120:135], v[156:159], v[12:15], 0
	v_mfma_f32_32x32x16_bf16 v[226:241], v[156:159], v[20:23], 0
	v_fma_f32 v70, v30, v34, v92
	v_fma_f32 v71, v30, v35, v108
	v_fma_f32 v72, v10, v35, v70
	v_fma_f32 v73, v11, v34, v71
	v_fma_f32 v70, v30, v72, v93
	v_fma_f32 v71, v30, v73, v109
	v_fma_f32 v34, v10, v73, v70
	v_fma_f32 v35, v11, v72, v71
	v_fma_f32 v70, v30, v34, v94
	v_fma_f32 v71, v30, v35, v110
	v_fma_f32 v72, v10, v35, v70
	v_fma_f32 v73, v11, v34, v71
	v_fma_f32 v70, v30, v72, v95
	v_fma_f32 v71, v30, v73, v111
	v_fma_f32 v34, v10, v73, v70
	v_fma_f32 v35, v11, v72, v71
	v_mfma_f32_32x32x16_bf16 v[120:135], v[200:203], v[16:19], v[120:135]
	v_mfma_f32_32x32x16_bf16 v[226:241], v[200:203], v[24:27], v[226:241]
	v_fma_f32 v70, v30, v34, v96
	v_fma_f32 v71, v30, v35, v112
	v_fma_f32 v72, v10, v35, v70
	v_fma_f32 v73, v11, v34, v71
	v_fma_f32 v70, v30, v72, v97
	v_fma_f32 v71, v30, v73, v113
	v_fma_f32 v34, v10, v73, v70
	v_fma_f32 v35, v11, v72, v71
	v_fma_f32 v70, v30, v34, v98
	v_fma_f32 v71, v30, v35, v114
	v_fma_f32 v72, v10, v35, v70
	v_fma_f32 v73, v11, v34, v71
	v_fma_f32 v70, v30, v72, v99
	v_fma_f32 v71, v30, v73, v115
	v_fma_f32 v34, v10, v73, v70
	v_fma_f32 v35, v11, v72, v71
	v_fma_f32 v70, v30, v34, v100
	v_fma_f32 v71, v30, v35, v116
	v_fma_f32 v72, v10, v35, v70
	v_fma_f32 v73, v11, v34, v71
	v_fma_f32 v70, v30, v72, v101
	v_fma_f32 v71, v30, v73, v117
	v_fma_f32 v34, v10, v73, v70
	v_fma_f32 v35, v11, v72, v71
	v_fma_f32 v70, v30, v34, v102
	v_fma_f32 v71, v30, v35, v118
	v_fma_f32 v72, v10, v35, v70
	v_fma_f32 v73, v11, v34, v71
	v_fma_f32 v70, v30, v72, v103
	v_fma_f32 v71, v30, v73, v119
	v_fma_f32 v34, v10, v73, v70
	v_fma_f32 v35, v11, v72, v71
	s_waitcnt vmcnt(9)
	ds_write_b64 v146, v[46:47]
	ds_read_b128 v[156:159], v196
	ds_read_b128 v[200:203], v197
	global_load_dwordx2 v[40:41], v[54:55], off
	v_lshl_add_u64 v[54:55], v[54:55], 0, s[20:21]
	s_cmp_eq_u32 s12, 0
	s_cbranch_scc1 .Lp1_skip
	v_cvt_pk_bf16_f32 v82, v74, v75
	v_cvt_pk_bf16_f32 v83, v76, v77
	v_cvt_pk_bf16_f32 v84, v78, v79
	v_cvt_pk_bf16_f32 v85, v80, v81
	global_store_dwordx4 v[58:59], v[82:85], off nt
	s_mov_b64 s[22:23], 0x200000
	v_lshl_add_u64 v[58:59], v[58:59], 0, s[22:23]
	s_branch .Lp1_join

; #define LAS __attribute__((address_space(3)))
; __device__ __forceinline__ unsigned cvt_pk_bf16(float lo, float hi) { const f32x2 v = {lo, hi}; return __builtin_bit_cast(unsigned, __builtin_convertvector(v, bfx2_t)); }
; __device__ __forceinline__ void conv_p(const Params& P, int l) {
;     ...
;         for (int q = 0; q < 4; ++q) { a[q] = *(const f32x4*)(src + (i + q * stride) * 8); b[q] = *(const f32x4*)(src + (i + q * stride) * 8 + 4); }
; template <int PASS> __device__ void ssm_pass(const Params& P, int l, LAS unsigned char* lds) {
;     ...
;         for (int mt = 0; mt < 64; ++mt) {
;             u32x2 unext = ucur; if (mt < 63) unext = *(const u32x2*)(zrow + (size_t)(mt + 1) * 16 * DM);
;             const bf16x4 af = __builtin_bit_cast(bf16x4, ucur);
;             f32x4 d[8];
; #pragma unroll
;             for (int t = 0; t < 8; ++t) d[t] = __builtin_amdgcn_mfma_f32_16x16x16bf16_1k(af, bf[t], (f32x4){0.f, 0.f, 0.f, 0.f}, 0, 0, 0);
; #pragma unroll
;             for (int tq = 0; tq < 4; ++tq)
; #pragma unroll
;                 for (int j = 0; j < 4; ++j) *(LAS f32x2*)(BU + (4 * fq + j) * 528 + (16 * tq + fr) * 8) = (f32x2){d[tq][j], d[tq + 4][j]};
;             asm volatile("s_waitcnt lgkmcnt(0)" ::: "memory");
; #pragma unroll
;             for (int j = 0; j < 16; ++j) {
;                 const f32x2 bu = *(const LAS f32x2*)(BU + j * 528 + lane * 8);
;                 sv = __builtin_elementwise_fma(ayn, __builtin_shufflevector(sv, sv, 1, 0), __builtin_elementwise_fma(axx, sv, bu));
;                 if (PASS == 2) *(LAS unsigned*)(SI + j * 272 + lane * 4) = cvt_pk_bf16(sv.x, sv.y);
;             }
.Lp1_join:
	v_fma_f32 v70, v30, v34, v120
	v_fma_f32 v71, v30, v35, v226
	v_fma_f32 v72, v10, v35, v70
	v_fma_f32 v73, v11, v34, v71
	v_fma_f32 v70, v30, v72, v121
	v_fma_f32 v71, v30, v73, v227
	v_fma_f32 v34, v10, v73, v70
	v_fma_f32 v35, v11, v72, v71
	v_fma_f32 v70, v30, v34, v122
	v_fma_f32 v71, v30, v35, v228
	v_fma_f32 v72, v10, v35, v70
	v_fma_f32 v73, v11, v34, v71
	v_fma_f32 v70, v30, v72, v123
	v_fma_f32 v71, v30, v73, v229
	v_fma_f32 v34, v10, v73, v70
	v_fma_f32 v35, v11, v72, v71
	s_waitcnt lgkmcnt(0)
	v_mfma_f32_32x32x16_bf16 v[88:103], v[156:159], v[12:15], 0
	v_mfma_f32_32x32x16_bf16 v[104:119], v[156:159], v[20:23], 0
	v_fma_f32 v70, v30, v34, v124
	v_fma_f32 v71, v30, v35, v230
	v_fma_f32 v72, v10, v35, v70
	v_fma_f32 v73, v11, v34, v71
	v_fma_f32 v70, v30, v72, v125
	v_fma_f32 v71, v30, v73, v231
	v_fma_f32 v34, v10, v73, v70
	v_fma_f32 v35, v11, v72, v71
	v_fma_f32 v70, v30, v34, v126
	v_fma_f32 v71, v30, v35, v232
	v_fma_f32 v72, v10, v35, v70
	v_fma_f32 v73, v11, v34, v71
	v_fma_f32 v70, v30, v72, v127
	v_fma_f32 v71, v30, v73, v233
	v_fma_f32 v34, v10, v73, v70
	v_fma_f32 v35, v11, v72, v71
	v_mfma_f32_32x32x16_bf16 v[88:103], v[200:203], v[16:19], v[88:103]
	v_mfma_f32_32x32x16_bf16 v[104:119], v[200:203], v[24:27], v[104:119]
	v_fma_f32 v70, v30, v34, v128
	v_fma_f32 v71, v30, v35, v234
	v_fma_f32 v72, v10, v35, v70
	v_fma_f32 v73, v11, v34, v71
	v_fma_f32 v70, v30, v72, v129
	v_fma_f32 v71, v30, v73, v235
	v_fma_f32 v34, v10, v73, v70
	v_fma_f32 v35, v11, v72, v71
	v_fma_f32 v70, v30, v34, v130
	v_fma_f32 v71, v30, v35, v236
	v_fma_f32 v72, v10, v35, v70
	v_fma_f32 v73, v11, v34, v71
	v_fma_f32 v70, v30, v72, v131
	v_fma_f32 v71, v30, v73, v237
	v_fma_f32 v34, v10, v73, v70
	v_fma_f32 v35, v11, v72, v71
	v_fma_f32 v70, v30, v34, v132
	v_fma_f32 v71, v30, v35, v238
	v_fma_f32 v72, v10, v35, v70
	v_fma_f32 v73, v11, v34, v71
	v_fma_f32 v70, v30, v72, v133
	v_fma_f32 v71, v30, v73, v239
	v_fma_f32 v34, v10, v73, v70
	v_fma_f32 v35, v11, v72, v71
	v_fma_f32 v70, v30, v34, v134
	v_fma_f32 v71, v30, v35, v240
	v_fma_f32 v72, v10, v35, v70
	v_fma_f32 v73, v11, v34, v71
	v_fma_f32 v70, v30, v72, v135
	v_fma_f32 v71, v30, v73, v241
	v_fma_f32 v34, v10, v73, v70
	v_fma_f32 v35, v11, v72, v71
	s_waitcnt vmcnt(9)
	ds_write_b64 v146, v[48:49]
	ds_read_b128 v[156:159], v196
	ds_read_b128 v[200:203], v197
	global_load_dwordx2 v[42:43], v[54:55], off
	v_lshl_add_u64 v[54:55], v[54:55], 0, s[20:21]
	global_load_dwordx4 v[74:77], v[56:57], off nt
	v_fma_f32 v70, v30, v34, v88
	v_fma_f32 v71, v30, v35, v104
	v_fma_f32 v72, v10, v35, v70
	v_fma_f32 v73, v11, v34, v71
	v_fma_f32 v70, v30, v72, v89
	v_fma_f32 v71, v30, v73, v105
	v_fma_f32 v34, v10, v73, v70
	v_fma_f32 v35, v11, v72, v71
	v_fma_f32 v70, v30, v34, v90
	v_fma_f32 v71, v30, v35, v106
	v_fma_f32 v72, v10, v35, v70
	v_fma_f32 v73, v11, v34, v71
	v_fma_f32 v70, v30, v72, v91
	v_fma_f32 v71, v30, v73, v107
	v_fma_f32 v34, v10, v73, v70
	v_fma_f32 v35, v11, v72, v71
	s_waitcnt lgkmcnt(0)
	v_mfma_f32_32x32x16_bf16 v[120:135], v[156:159], v[12:15], 0
	v_mfma_f32_32x32x16_bf16 v[226:241], v[156:159], v[20:23], 0
	v_fma_f32 v70, v30, v34, v92
	v_fma_f32 v71, v30, v35, v108
	v_fma_f32 v72, v10, v35, v70
	v_fma_f32 v73, v11, v34, v71
	v_fma_f32 v70, v30, v72, v93
	v_fma_f32 v71, v30, v73, v109
	v_fma_f32 v34, v10, v73, v70
	v_fma_f32 v35, v11, v72, v71
	v_fma_f32 v70, v30, v34, v94
	v_fma_f32 v71, v30, v35, v110
	v_fma_f32 v72, v10, v35, v70
	v_fma_f32 v73, v11, v34, v71
	v_fma_f32 v70, v30, v72, v95
	v_fma_f32 v71, v30, v73, v111
	v_fma_f32 v34, v10, v73, v70
	v_fma_f32 v35, v11, v72, v71
	v_mfma_f32_32x32x16_bf16 v[120:135], v[200:203], v[16:19], v[120:135]
	v_mfma_f32_32x32x16_bf16 v[226:241], v[200:203], v[24:27], v[226:241]
	v_fma_f32 v70, v30, v34, v96
	v_fma_f32 v71, v30, v35, v112
	v_fma_f32 v72, v10, v35, v70
	v_fma_f32 v73, v11, v34, v71
	v_fma_f32 v70, v30, v72, v97
	v_fma_f32 v71, v30, v73, v113
	v_fma_f32 v34, v10, v73, v70
	v_fma_f32 v35, v11, v72, v71
	v_fma_f32 v70, v30, v34, v98
	v_fma_f32 v71, v30, v35, v114
	v_fma_f32 v72, v10, v35, v70
	v_fma_f32 v73, v11, v34, v71
	v_fma_f32 v70, v30, v72, v99
	v_fma_f32 v71, v30, v73, v115
	v_fma_f32 v34, v10, v73, v70
	v_fma_f32 v35, v11, v72, v71
	v_fma_f32 v70, v30, v34, v100
	v_fma_f32 v71, v30, v35, v116
	v_fma_f32 v72, v10, v35, v70
	v_fma_f32 v73, v11, v34, v71
	v_fma_f32 v70, v30, v72, v101
	v_fma_f32 v71, v30, v73, v117
	v_fma_f32 v34, v10, v73, v70
	v_fma_f32 v35, v11, v72, v71
	v_fma_f32 v70, v30, v34, v102
	v_fma_f32 v71, v30, v35, v118
	v_fma_f32 v72, v10, v35, v70
	v_fma_f32 v73, v11, v34, v71
	v_fma_f32 v70, v30, v72, v103
	v_fma_f32 v71, v30, v73, v119
	v_fma_f32 v34, v10, v73, v70
	v_fma_f32 v35, v11, v72, v71
	s_waitcnt vmcnt(9)
	ds_write_b64 v146, v[50:51]
	ds_read_b128 v[156:159], v196
	ds_read_b128 v[200:203], v197
	global_load_dwordx2 v[44:45], v[54:55], off
	v_lshl_add_u64 v[54:55], v[54:55], 0, s[20:21]
	global_load_dwordx4 v[78:81], v[56:57], off offset:16 nt
	s_mov_b64 s[22:23], 0x400000
	v_lshl_add_u64 v[56:57], v[56:57], 0, s[22:23]
	v_fma_f32 v70, v30, v34, v120
	v_fma_f32 v71, v30, v35, v226
	v_fma_f32 v72, v10, v35, v70
	v_fma_f32 v73, v11, v34, v71
	v_fma_f32 v70, v30, v72, v121
	v_fma_f32 v71, v30, v73, v227
	v_fma_f32 v34, v10, v73, v70
	v_fma_f32 v35, v11, v72, v71
	v_fma_f32 v70, v30, v34, v122
	v_fma_f32 v71, v30, v35, v228
	v_fma_f32 v72, v10, v35, v70
	v_fma_f32 v73, v11, v34, v71
	v_fma_f32 v70, v30, v72, v123
	v_fma_f32 v71, v30, v73, v229
	v_fma_f32 v34, v10, v73, v70
	v_fma_f32 v35, v11, v72, v71
	s_waitcnt lgkmcnt(0)
; #define LAS __attribute__((address_space(3)))
; __device__ __forceinline__ unsigned cvt_pk_bf16(float lo, float hi) { const f32x2 v = {lo, hi}; return __builtin_bit_cast(unsigned, __builtin_convertvector(v, bfx2_t)); }
; __device__ __forceinline__ void conv_p(const Params& P, int l) {
;     ...
;         for (int q = 0; q < 4; ++q) { u32x4 w; w.x = cvt_pk_bf16(a[q][0], a[q][1]); w.y = cvt_pk_bf16(a[q][2], a[q][3]); w.z = cvt_pk_bf16(b[q][0], b[q][1]); w.w = cvt_pk_bf16(b[q][2], b[q][3]);
;             *(u32x4*)(dst + (i + q * stride) * 8) = w; }
; template <int PASS> __device__ void ssm_pass(const Params& P, int l, LAS unsigned char* lds) {
;     ...
;         for (int mt = 0; mt < 64; ++mt) {
;             u32x2 unext = ucur; if (mt < 63) unext = *(const u32x2*)(zrow + (size_t)(mt + 1) * 16 * DM);
;             const bf16x4 af = __builtin_bit_cast(bf16x4, ucur);
;             f32x4 d[8];
; #pragma unroll
;             for (int t = 0; t < 8; ++t) d[t] = __builtin_amdgcn_mfma_f32_16x16x16bf16_1k(af, bf[t], (f32x4){0.f, 0.f, 0.f, 0.f}, 0, 0, 0);
; #pragma unroll
;             for (int tq = 0; tq < 4; ++tq)
; #pragma unroll
;                 for (int j = 0; j < 4; ++j) *(LAS f32x2*)(BU + (4 * fq + j) * 528 + (16 * tq + fr) * 8) = (f32x2){d[tq][j], d[tq + 4][j]};
;             asm volatile("s_waitcnt lgkmcnt(0)" ::: "memory");
; #pragma unroll
;             for (int j = 0; j < 16; ++j) {
;                 const f32x2 bu = *(const LAS f32x2*)(BU + j * 528 + lane * 8);
;                 sv = __builtin_elementwise_fma(ayn, __builtin_shufflevector(sv, sv, 1, 0), __builtin_elementwise_fma(axx, sv, bu));
;                 if (PASS == 2) *(LAS unsigned*)(SI + j * 272 + lane * 4) = cvt_pk_bf16(sv.x, sv.y);
;             }
	v_mfma_f32_32x32x16_bf16 v[88:103], v[156:159], v[12:15], 0
	v_mfma_f32_32x32x16_bf16 v[104:119], v[156:159], v[20:23], 0
	v_fma_f32 v70, v30, v34, v124
	v_fma_f32 v71, v30, v35, v230
	v_fma_f32 v72, v10, v35, v70
	v_fma_f32 v73, v11, v34, v71
	v_fma_f32 v70, v30, v72, v125
	v_fma_f32 v71, v30, v73, v231
	v_fma_f32 v34, v10, v73, v70
	v_fma_f32 v35, v11, v72, v71
	v_fma_f32 v70, v30, v34, v126
	v_fma_f32 v71, v30, v35, v232
	v_fma_f32 v72, v10, v35, v70
	v_fma_f32 v73, v11, v34, v71
	v_fma_f32 v70, v30, v72, v127
	v_fma_f32 v71, v30, v73, v233
	v_fma_f32 v34, v10, v73, v70
	v_fma_f32 v35, v11, v72, v71
	v_mfma_f32_32x32x16_bf16 v[88:103], v[200:203], v[16:19], v[88:103]
	v_mfma_f32_32x32x16_bf16 v[104:119], v[200:203], v[24:27], v[104:119]
	v_fma_f32 v70, v30, v34, v128
	v_fma_f32 v71, v30, v35, v234
	v_fma_f32 v72, v10, v35, v70
	v_fma_f32 v73, v11, v34, v71
	v_fma_f32 v70, v30, v72, v129
	v_fma_f32 v71, v30, v73, v235
	v_fma_f32 v34, v10, v73, v70
	v_fma_f32 v35, v11, v72, v71
	v_fma_f32 v70, v30, v34, v130
	v_fma_f32 v71, v30, v35, v236
	v_fma_f32 v72, v10, v35, v70
	v_fma_f32 v73, v11, v34, v71
	v_fma_f32 v70, v30, v72, v131
	v_fma_f32 v71, v30, v73, v237
	v_fma_f32 v34, v10, v73, v70
	v_fma_f32 v35, v11, v72, v71
	v_fma_f32 v70, v30, v34, v132
	v_fma_f32 v71, v30, v35, v238
	v_fma_f32 v72, v10, v35, v70
	v_fma_f32 v73, v11, v34, v71
	v_fma_f32 v70, v30, v72, v133
	v_fma_f32 v71, v30, v73, v239
	v_fma_f32 v34, v10, v73, v70
	v_fma_f32 v35, v11, v72, v71
	v_fma_f32 v70, v30, v34, v134
	v_fma_f32 v71, v30, v35, v240
	v_fma_f32 v72, v10, v35, v70
	v_fma_f32 v73, v11, v34, v71
	v_fma_f32 v70, v30, v72, v135
	v_fma_f32 v71, v30, v73, v241
	v_fma_f32 v34, v10, v73, v70
	v_fma_f32 v35, v11, v72, v71
	s_waitcnt vmcnt(9)
	ds_write_b64 v146, v[52:53]
	ds_read_b128 v[156:159], v196
	ds_read_b128 v[200:203], v197
	global_load_dwordx2 v[46:47], v[54:55], off
	v_lshl_add_u64 v[54:55], v[54:55], 0, s[20:21]
	global_load_dwordx2 v[144:145], v[54:55], off
	v_fma_f32 v70, v30, v34, v88
	v_fma_f32 v71, v30, v35, v104
	v_fma_f32 v72, v10, v35, v70
	v_fma_f32 v73, v11, v34, v71
	v_fma_f32 v70, v30, v72, v89
	v_fma_f32 v71, v30, v73, v105
	v_fma_f32 v34, v10, v73, v70
	v_fma_f32 v35, v11, v72, v71
	v_fma_f32 v70, v30, v34, v90
	v_fma_f32 v71, v30, v35, v106
	v_fma_f32 v72, v10, v35, v70
	v_fma_f32 v73, v11, v34, v71
	v_fma_f32 v70, v30, v72, v91
	v_fma_f32 v71, v30, v73, v107
	v_fma_f32 v34, v10, v73, v70
	v_fma_f32 v35, v11, v72, v71
	s_waitcnt lgkmcnt(0)
	v_mfma_f32_32x32x16_bf16 v[120:135], v[156:159], v[12:15], 0
	v_mfma_f32_32x32x16_bf16 v[226:241], v[156:159], v[20:23], 0
	v_fma_f32 v70, v30, v34, v92
	v_fma_f32 v71, v30, v35, v108
	v_fma_f32 v72, v10, v35, v70
	v_fma_f32 v73, v11, v34, v71
	v_fma_f32 v70, v30, v72, v93
	v_fma_f32 v71, v30, v73, v109
	v_fma_f32 v34, v10, v73, v70
	v_fma_f32 v35, v11, v72, v71
	v_fma_f32 v70, v30, v34, v94
	v_fma_f32 v71, v30, v35, v110
	v_fma_f32 v72, v10, v35, v70
	v_fma_f32 v73, v11, v34, v71
	v_fma_f32 v70, v30, v72, v95
	v_fma_f32 v71, v30, v73, v111
	v_fma_f32 v34, v10, v73, v70
	v_fma_f32 v35, v11, v72, v71
	v_mfma_f32_32x32x16_bf16 v[120:135], v[200:203], v[16:19], v[120:135]
	v_mfma_f32_32x32x16_bf16 v[226:241], v[200:203], v[24:27], v[226:241]
	v_fma_f32 v70, v30, v34, v96
	v_fma_f32 v71, v30, v35, v112
	v_fma_f32 v72, v10, v35, v70
	v_fma_f32 v73, v11, v34, v71
	v_fma_f32 v70, v30, v72, v97
	v_fma_f32 v71, v30, v73, v113
	v_fma_f32 v34, v10, v73, v70
	v_fma_f32 v35, v11, v72, v71
	v_fma_f32 v70, v30, v34, v98
	v_fma_f32 v71, v30, v35, v114
	v_fma_f32 v72, v10, v35, v70
	v_fma_f32 v73, v11, v34, v71
	v_fma_f32 v70, v30, v72, v99
	v_fma_f32 v71, v30, v73, v115
	v_fma_f32 v34, v10, v73, v70
	v_fma_f32 v35, v11, v72, v71
	v_fma_f32 v70, v30, v34, v100
	v_fma_f32 v71, v30, v35, v116
	v_fma_f32 v72, v10, v35, v70
	v_fma_f32 v73, v11, v34, v71
	v_fma_f32 v70, v30, v72, v101
	v_fma_f32 v71, v30, v73, v117
	v_fma_f32 v34, v10, v73, v70
	v_fma_f32 v35, v11, v72, v71
	v_fma_f32 v70, v30, v34, v102
	v_fma_f32 v71, v30, v35, v118
	v_fma_f32 v72, v10, v35, v70
	v_fma_f32 v73, v11, v34, v71
	v_fma_f32 v70, v30, v72, v103
	v_fma_f32 v71, v30, v73, v119
	v_fma_f32 v34, v10, v73, v70
	v_fma_f32 v35, v11, v72, v71
	s_waitcnt vmcnt(9)
	ds_write_b64 v146, v[36:37]
	ds_read_b128 v[156:159], v196
	ds_read_b128 v[200:203], v197
	global_load_dwordx2 v[48:49], v[54:55], off
	v_lshl_add_u64 v[54:55], v[54:55], 0, s[20:21]
	v_cvt_pk_bf16_f32 v82, v60, v61
	v_cvt_pk_bf16_f32 v83, v62, v63
	v_cvt_pk_bf16_f32 v84, v64, v65
	v_cvt_pk_bf16_f32 v85, v66, v67
	global_store_dwordx4 v[58:59], v[82:85], off nt
	s_mov_b64 s[22:23], 0x200000
	v_lshl_add_u64 v[58:59], v[58:59], 0, s[22:23]
	v_fma_f32 v70, v30, v34, v120
	v_fma_f32 v71, v30, v35, v226
	v_fma_f32 v72, v10, v35, v70
	v_fma_f32 v73, v11, v34, v71
	v_fma_f32 v70, v30, v72, v121
	v_fma_f32 v71, v30, v73, v227
	v_fma_f32 v34, v10, v73, v70
	v_fma_f32 v35, v11, v72, v71
	v_fma_f32 v70, v30, v34, v122
	v_fma_f32 v71, v30, v35, v228
	v_fma_f32 v72, v10, v35, v70
	v_fma_f32 v73, v11, v34, v71
	v_fma_f32 v70, v30, v72, v123
	v_fma_f32 v71, v30, v73, v229
	v_fma_f32 v34, v10, v73, v70
	v_fma_f32 v35, v11, v72, v71
	s_waitcnt lgkmcnt(0)
	v_mfma_f32_32x32x16_bf16 v[88:103], v[156:159], v[12:15], 0
	v_mfma_f32_32x32x16_bf16 v[104:119], v[156:159], v[20:23], 0
	v_fma_f32 v70, v30, v34, v124
	v_fma_f32 v71, v30, v35, v230
	v_fma_f32 v72, v10, v35, v70
	v_fma_f32 v73, v11, v34, v71
	v_fma_f32 v70, v30, v72, v125
	v_fma_f32 v71, v30, v73, v231
	v_fma_f32 v34, v10, v73, v70
	v_fma_f32 v35, v11, v72, v71
	v_fma_f32 v70, v30, v34, v126
	v_fma_f32 v71, v30, v35, v232
	v_fma_f32 v72, v10, v35, v70
	v_fma_f32 v73, v11, v34, v71
	v_fma_f32 v70, v30, v72, v127
	v_fma_f32 v71, v30, v73, v233
	v_fma_f32 v34, v10, v73, v70
	v_fma_f32 v35, v11, v72, v71
	v_mfma_f32_32x32x16_bf16 v[88:103], v[200:203], v[16:19], v[88:103]
	v_mfma_f32_32x32x16_bf16 v[104:119], v[200:203], v[24:27], v[104:119]
	v_fma_f32 v70, v30, v34, v128
	v_fma_f32 v71, v30, v35, v234
	v_fma_f32 v72, v10, v35, v70
	v_fma_f32 v73, v11, v34, v71
	v_fma_f32 v70, v30, v72, v129
	v_fma_f32 v71, v30, v73, v235
	v_fma_f32 v34, v10, v73, v70
	v_fma_f32 v35, v11, v72, v71
	v_fma_f32 v70, v30, v34, v130
	v_fma_f32 v71, v30, v35, v236
	v_fma_f32 v72, v10, v35, v70
	v_fma_f32 v73, v11, v34, v71
	v_fma_f32 v70, v30, v72, v131
	v_fma_f32 v71, v30, v73, v237
	v_fma_f32 v34, v10, v73, v70
	v_fma_f32 v35, v11, v72, v71
	v_fma_f32 v70, v30, v34, v132
	v_fma_f32 v71, v30, v35, v238
	v_fma_f32 v72, v10, v35, v70
	v_fma_f32 v73, v11, v34, v71
	v_fma_f32 v70, v30, v72, v133
	v_fma_f32 v71, v30, v73, v239
	v_fma_f32 v34, v10, v73, v70
	v_fma_f32 v35, v11, v72, v71
	v_fma_f32 v70, v30, v34, v134
	v_fma_f32 v71, v30, v35, v240
	v_fma_f32 v72, v10, v35, v70
	v_fma_f32 v73, v11, v34, v71
	v_fma_f32 v70, v30, v72, v135
	v_fma_f32 v71, v30, v73, v241
	v_fma_f32 v34, v10, v73, v70
	v_fma_f32 v35, v11, v72, v71
	s_add_u32 s12, s12, 8
	s_cmp_eq_u32 s12, 64
	s_cbranch_scc0 .Lp1_loop
; __device__ __forceinline__ unsigned cvt_pk_bf16(float lo, float hi) { const f32x2 v = {lo, hi}; return __builtin_bit_cast(unsigned, __builtin_convertvector(v, bfx2_t)); }
; __device__ __forceinline__ void conv_p(const Params& P, int l) {
;     ...
;         for (int q = 0; q < 4; ++q) { u32x4 w; w.x = cvt_pk_bf16(a[q][0], a[q][1]); w.y = cvt_pk_bf16(a[q][2], a[q][3]); w.z = cvt_pk_bf16(b[q][0], b[q][1]); w.w = cvt_pk_bf16(b[q][2], b[q][3]);
;             *(u32x4*)(dst + (i + q * stride) * 8) = w; }
	s_waitcnt vmcnt(0)
	v_cvt_pk_bf16_f32 v82, v74, v75
	v_cvt_pk_bf16_f32 v83, v76, v77
	v_cvt_pk_bf16_f32 v84, v78, v79
	v_cvt_pk_bf16_f32 v85, v80, v81
	global_store_dwordx4 v[58:59], v[82:85], off nt
	s_mov_b64 s[22:23], 0x200000
	v_lshl_add_u64 v[58:59], v[58:59], 0, s[22:23]
	s_waitcnt lgkmcnt(0)
	s_branch .LBB0_338
